# attention loop tail: score-minus-max and row sum with packed f32 adds, masked scores kept in accumulator pairs (144 VALU per iteration vs 161)
# baseline (speedup 1.0000x reference)
.LBB0_413:
	v_bitop3_b32 v64, s45, v142, v189 bitop3:0x36
	v_bitop3_b32 v72, s45, v143, v189 bitop3:0x36
	v_bitop3_b32 v80, s44, v142, v189 bitop3:0x36
	v_bitop3_b32 v88, s44, v143, v189 bitop3:0x36
	v_mad_i32_i24 v68, v64, s18, v122
	v_mad_i32_i24 v76, v72, s18, v122
	v_mad_i32_i24 v84, v80, s18, v122
	v_mad_i32_i24 v92, v88, s18, v122
	ds_read_b128 v[64:67], v68 offset:18496
	ds_read_b128 v[68:71], v68 offset:18432
	ds_read_b128 v[72:75], v76 offset:18496
	ds_read_b128 v[76:79], v76 offset:18432
	ds_read_b128 v[80:83], v84 offset:18496
	ds_read_b128 v[84:87], v84 offset:18432
	ds_read_b128 v[88:91], v92 offset:18496
	ds_read_b128 v[92:95], v92 offset:18432
	s_waitcnt lgkmcnt(0)
	v_mfma_f32_16x16x32_bf16 v[92:95], v[92:95], v[56:59], 0
	v_cmp_gt_u32_e64 s[60:61], s97, v160
	v_cmp_gt_u32_e64 s[62:63], s97, v161
	v_cmp_gt_u32_e64 s[64:65], s97, v162
	v_cmp_gt_u32_e64 s[72:73], s97, v163
	v_mfma_f32_16x16x32_bf16 v[108:111], v[88:91], v[60:63], v[92:95]
	s_cmp_lt_i32 s51, s42
	s_cselect_b32 s101, s97, 0
	s_cselect_b64 s[2:3], -1, 0
	s_cmp_lg_u64 s[2:3], 0
	v_mfma_f32_16x16x32_bf16 v[84:87], v[84:87], v[56:59], 0
	s_addc_u32 s44, s51, 0
	v_mov_b32_e32 v154, v96
	v_cmp_gt_u32_e64 s[74:75], s97, v164
	v_cmp_gt_u32_e64 s[92:93], s97, v165
	v_cmp_gt_u32_e64 s[94:95], s97, v166
	v_cmp_gt_u32_e64 s[98:99], s97, v167
	s_lshl_b32 s52, s44, 5
	s_lshr_b32 s45, s51, 2
	v_pk_mul_f32 v[108:109], v[108:109], v[126:127] op_sel_hi:[1,0]
	v_pk_mul_f32 v[110:111], v[110:111], v[126:127] op_sel_hi:[1,0]
	v_pk_fma_f32 v[108:109], v[160:161], v[128:129], v[108:109] op_sel:[0,1,0] op_sel_hi:[1,1,1] neg_lo:[0,1,0] neg_hi:[0,1,0]
	v_pk_fma_f32 v[110:111], v[162:163], v[128:129], v[110:111] op_sel:[0,1,0] op_sel_hi:[1,1,1] neg_lo:[0,1,0] neg_hi:[0,1,0]
	v_mfma_f32_16x16x32_bf16 v[104:107], v[80:83], v[60:63], v[84:87]
	v_cndmask_b32_e64 v108, v144, v108, s[60:61]
	v_cndmask_b32_e64 v109, v144, v109, s[62:63]
	v_cndmask_b32_e64 v110, v144, v110, s[64:65]
	v_cndmask_b32_e64 v111, v144, v111, s[72:73]
	v_mfma_f32_16x16x32_bf16 v[76:79], v[76:79], v[56:59], 0
	v_max3_f32 v157, v108, s30, v109
	v_max3_f32 v157, v157, v110, v111
	v_pk_add_f32 v[160:161], v[160:161], v[176:177] op_sel_hi:[1,0]
	v_pk_add_f32 v[162:163], v[162:163], v[176:177] op_sel_hi:[1,0]
	v_cmp_gt_u32_e64 s[60:61], s101, v168
	v_cmp_gt_u32_e64 s[62:63], s101, v169
	v_cmp_gt_u32_e64 s[64:65], s101, v170
	v_cmp_gt_u32_e64 s[72:73], s101, v171
	s_xor_b32 s45, s45, s17
	s_lshl_b32 s45, s45, 7
	v_pk_mul_f32 v[104:105], v[104:105], v[126:127] op_sel_hi:[1,0]
	v_pk_mul_f32 v[106:107], v[106:107], v[126:127] op_sel_hi:[1,0]
	v_pk_fma_f32 v[104:105], v[164:165], v[128:129], v[104:105] op_sel:[0,1,0] op_sel_hi:[1,1,1] neg_lo:[0,1,0] neg_hi:[0,1,0]
	v_pk_fma_f32 v[106:107], v[166:167], v[128:129], v[106:107] op_sel:[0,1,0] op_sel_hi:[1,1,1] neg_lo:[0,1,0] neg_hi:[0,1,0]
	v_mfma_f32_16x16x32_bf16 v[100:103], v[72:75], v[60:63], v[76:79]
	v_cndmask_b32_e64 v104, v144, v104, s[74:75]
	v_cndmask_b32_e64 v105, v144, v105, s[92:93]
	v_cndmask_b32_e64 v106, v144, v106, s[94:95]
	v_cndmask_b32_e64 v107, v144, v107, s[98:99]
	v_mfma_f32_16x16x32_bf16 v[68:71], v[68:71], v[56:59], 0
	v_max3_f32 v157, v157, v104, v105
	v_max3_f32 v157, v157, v106, v107
	v_pk_add_f32 v[164:165], v[164:165], v[176:177] op_sel_hi:[1,0]
	v_pk_add_f32 v[166:167], v[166:167], v[176:177] op_sel_hi:[1,0]
	v_cmp_gt_u32_e64 s[74:75], s101, v172
	v_cmp_gt_u32_e64 s[92:93], s101, v173
	v_cmp_gt_u32_e64 s[94:95], s101, v174
	v_cmp_gt_u32_e64 s[98:99], s101, v175
	s_and_b32 s45, s45, 0x80
	s_and_b32 s50, s43, 0x60
	v_pk_mul_f32 v[100:101], v[100:101], v[126:127] op_sel_hi:[1,0]
	v_pk_mul_f32 v[102:103], v[102:103], v[126:127] op_sel_hi:[1,0]
	v_pk_fma_f32 v[100:101], v[168:169], v[128:129], v[100:101] op_sel:[0,1,0] op_sel_hi:[1,1,1] neg_lo:[0,1,0] neg_hi:[0,1,0]
	v_pk_fma_f32 v[102:103], v[170:171], v[128:129], v[102:103] op_sel:[0,1,0] op_sel_hi:[1,1,1] neg_lo:[0,1,0] neg_hi:[0,1,0]
	v_mfma_f32_16x16x32_bf16 v[200:203], v[64:67], v[60:63], v[68:71]
	v_cndmask_b32_e64 v100, v144, v100, s[60:61]
	v_cndmask_b32_e64 v101, v144, v101, s[62:63]
	v_cndmask_b32_e64 v102, v144, v102, s[64:65]
	v_cndmask_b32_e64 v103, v144, v103, s[72:73]
	v_max3_f32 v157, v157, v100, v101
	v_max3_f32 v157, v157, v102, v103
	v_pk_add_f32 v[168:169], v[168:169], v[176:177] op_sel_hi:[1,0]
	v_pk_add_f32 v[170:171], v[170:171], v[176:177] op_sel_hi:[1,0]
	s_or_b32 s45, s45, s50
	s_lshr_b32 s50, s44, 2
	s_xor_b32 s50, s50, s17
	v_bitop3_b32 v158, s45, v123, v143 bitop3:0xde
	v_bitop3_b32 v159, s45, v130, v143 bitop3:0xde
	v_pk_mul_f32 v[200:201], v[200:201], v[126:127] op_sel_hi:[1,0]
	v_pk_mul_f32 v[202:203], v[202:203], v[126:127] op_sel_hi:[1,0]
	v_pk_fma_f32 v[200:201], v[172:173], v[128:129], v[200:201] op_sel:[0,1,0] op_sel_hi:[1,1,1] neg_lo:[0,1,0] neg_hi:[0,1,0]
	v_pk_fma_f32 v[202:203], v[174:175], v[128:129], v[202:203] op_sel:[0,1,0] op_sel_hi:[1,1,1] neg_lo:[0,1,0] neg_hi:[0,1,0]
	v_cndmask_b32_e64 v200, v144, v200, s[74:75]
	v_cndmask_b32_e64 v201, v144, v201, s[92:93]
	v_cndmask_b32_e64 v202, v144, v202, s[94:95]
	v_cndmask_b32_e64 v203, v144, v203, s[98:99]
	v_max3_f32 v157, v157, v200, v201
	v_max3_f32 v157, v157, v202, v203
	v_pk_add_f32 v[172:173], v[172:173], v[176:177] op_sel_hi:[1,0]
	v_pk_add_f32 v[174:175], v[174:175], v[176:177] op_sel_hi:[1,0]
	ds_bpermute_b32 v156, v150, v157
	s_lshl_b32 s50, s50, 7
	v_mad_u32_u24 v76, v158, s18, 0
	v_mad_u32_u24 v78, v159, s18, 0
	s_and_b32 s50, s50, 0x80
	s_and_b32 s44, s52, 0x60
	s_or_b32 s44, s50, s44
	v_add_u32_e32 v72, v76, v125
	v_add_u32_e32 v74, v78, v125
	v_add_u32_e32 v76, v76, v131
	v_add_u32_e32 v78, v78, v131
	s_waitcnt lgkmcnt(0)
	v_max_f32_e32 v156, v156, v156
	v_max_f32_e32 v157, v157, v156
	ds_bpermute_b32 v156, v151, v157
	v_bitop3_b32 v158, s44, v123, v143 bitop3:0xde
	v_bitop3_b32 v159, s44, v130, v143 bitop3:0xde
	v_mad_u32_u24 v92, v158, s18, 0
	v_mad_u32_u24 v94, v159, s18, 0
	v_add_u32_e32 v88, v92, v125
	v_add_u32_e32 v90, v94, v125
	v_add_u32_e32 v92, v92, v131
	v_add_u32_e32 v94, v94, v131
	s_waitcnt lgkmcnt(0)
	v_max3_f32 v96, v154, v157, v156
	ds_read_b64_tr_b16 v[70:71], v74 offset:55296
	ds_read_b64_tr_b16 v[66:67], v74 offset:55328
	ds_read_b64_tr_b16 v[68:69], v72 offset:55296
	ds_read_b64_tr_b16 v[64:65], v72 offset:55328
	ds_read_b64_tr_b16 v[72:73], v72 offset:55360
	ds_read_b64_tr_b16 v[74:75], v74 offset:55360
	ds_read_b64_tr_b16 v[76:77], v76 offset:55296
	ds_read_b64_tr_b16 v[78:79], v78 offset:55296
	v_sub_f32_e32 v155, v154, v96
	v_pk_add_f32 v[108:109], v[108:109], v[96:97] op_sel_hi:[1,0] neg_lo:[0,1] neg_hi:[0,1]
	v_pk_add_f32 v[110:111], v[110:111], v[96:97] op_sel_hi:[1,0] neg_lo:[0,1] neg_hi:[0,1]
	v_pk_add_f32 v[104:105], v[104:105], v[96:97] op_sel_hi:[1,0] neg_lo:[0,1] neg_hi:[0,1]
	v_pk_add_f32 v[106:107], v[106:107], v[96:97] op_sel_hi:[1,0] neg_lo:[0,1] neg_hi:[0,1]
	ds_read_b64_tr_b16 v[86:87], v90 offset:55296
	ds_read_b64_tr_b16 v[82:83], v90 offset:55328
	ds_read_b64_tr_b16 v[84:85], v88 offset:55296
	ds_read_b64_tr_b16 v[80:81], v88 offset:55328
	ds_read_b64_tr_b16 v[88:89], v88 offset:55360
	ds_read_b64_tr_b16 v[90:91], v90 offset:55360
	ds_read_b64_tr_b16 v[92:93], v92 offset:55296
	ds_read_b64_tr_b16 v[94:95], v94 offset:55296
	v_exp_f32_e32 v108, v108
	v_exp_f32_e32 v109, v109
	v_exp_f32_e32 v110, v110
	v_exp_f32_e32 v111, v111
	v_exp_f32_e32 v154, v155
	v_exp_f32_e32 v104, v104
	v_exp_f32_e32 v105, v105
	v_exp_f32_e32 v106, v106
	v_exp_f32_e32 v107, v107
	v_pk_add_f32 v[100:101], v[100:101], v[96:97] op_sel_hi:[1,0] neg_lo:[0,1] neg_hi:[0,1]
	v_pk_add_f32 v[102:103], v[102:103], v[96:97] op_sel_hi:[1,0] neg_lo:[0,1] neg_hi:[0,1]
	v_pk_add_f32 v[200:201], v[200:201], v[96:97] op_sel_hi:[1,0] neg_lo:[0,1] neg_hi:[0,1]
	v_pk_add_f32 v[202:203], v[202:203], v[96:97] op_sel_hi:[1,0] neg_lo:[0,1] neg_hi:[0,1]
	s_add_i32 s50, s51, 2
	s_min_i32 s44, s50, s42
	s_add_i32 s45, s51, 3
	s_lshr_b32 s51, s44, 2
	s_xor_b32 s51, s51, s17
	v_exp_f32_e32 v100, v100
	v_exp_f32_e32 v101, v101
	v_exp_f32_e32 v102, v102
	v_exp_f32_e32 v103, v103
	v_cvt_pk_bf16_f32 v212, v108, v109
	v_cvt_pk_bf16_f32 v213, v110, v111
	v_cvt_pk_bf16_f32 v214, v104, v105
	v_cvt_pk_bf16_f32 v215, v106, v107
	v_pk_mul_f32 v[54:55], v[54:55], v[154:155] op_sel_hi:[1,0]
	v_pk_mul_f32 v[52:53], v[52:53], v[154:155] op_sel_hi:[1,0]
	v_pk_mul_f32 v[50:51], v[50:51], v[154:155] op_sel_hi:[1,0]
	v_pk_mul_f32 v[48:49], v[48:49], v[154:155] op_sel_hi:[1,0]
	v_pk_mul_f32 v[46:47], v[46:47], v[154:155] op_sel_hi:[1,0]
	v_pk_mul_f32 v[44:45], v[44:45], v[154:155] op_sel_hi:[1,0]
	v_pk_mul_f32 v[42:43], v[42:43], v[154:155] op_sel_hi:[1,0]
	v_pk_mul_f32 v[40:41], v[40:41], v[154:155] op_sel_hi:[1,0]
	s_lshl_b32 s51, s51, 7
	s_lshl_b32 s44, s44, 5
	s_waitcnt lgkmcnt(13)
	v_mfma_f32_16x16x32_bf16 v[52:55], v[68:71], v[212:215], v[52:55]
	v_exp_f32_e32 v200, v200
	v_exp_f32_e32 v201, v201
	s_min_i32 s45, s45, s42
	s_and_b32 s51, s51, 0x80
	s_and_b32 s44, s44, 0x60
	s_waitcnt lgkmcnt(12)
	v_mfma_f32_16x16x32_bf16 v[48:51], v[64:67], v[212:215], v[48:51]
	v_exp_f32_e32 v202, v202
	v_exp_f32_e32 v203, v203
	s_or_b32 s44, s51, s44
	s_lshr_b32 s51, s45, 2
	s_waitcnt lgkmcnt(10)
	v_mfma_f32_16x16x32_bf16 v[44:47], v[72:75], v[212:215], v[44:47]
	v_pk_add_f32 v[204:205], v[108:109], v[110:111]
	v_pk_add_f32 v[206:207], v[104:105], v[106:107]
	s_xor_b32 s51, s51, s17
	s_waitcnt lgkmcnt(8)
	v_mfma_f32_16x16x32_bf16 v[40:43], v[76:79], v[212:215], v[40:43]
	v_cvt_pk_bf16_f32 v216, v100, v101
	v_cvt_pk_bf16_f32 v217, v102, v103
	v_cvt_pk_bf16_f32 v218, v200, v201
	v_cvt_pk_bf16_f32 v219, v202, v203
	v_pk_add_f32 v[210:211], v[100:101], v[102:103]
	v_pk_add_f32 v[156:157], v[200:201], v[202:203]
	s_lshl_b32 s51, s51, 7
	s_lshl_b32 s45, s45, 5
	s_waitcnt lgkmcnt(5)
	v_mfma_f32_16x16x32_bf16 v[52:55], v[84:87], v[216:219], v[52:55]
	v_pk_add_f32 v[204:205], v[204:205], v[206:207]
	v_pk_add_f32 v[210:211], v[210:211], v[156:157]
	s_and_b32 s51, s51, 0x80
	s_and_b32 s45, s45, 0x60
	s_waitcnt lgkmcnt(4)
	v_mfma_f32_16x16x32_bf16 v[48:51], v[80:83], v[216:219], v[48:51]
	v_pk_add_f32 v[204:205], v[204:205], v[210:211]
	s_or_b32 s45, s51, s45
	s_add_i32 s43, s43, 64
	s_waitcnt lgkmcnt(2)
	v_mfma_f32_16x16x32_bf16 v[44:47], v[88:91], v[216:219], v[44:47]
	v_add_f32_e32 v204, v204, v205
	v_subrev_u32_e32 v152, 64, v152
	s_cmp_gt_i32 s50, s42
	s_waitcnt lgkmcnt(0)
	v_mfma_f32_16x16x32_bf16 v[40:43], v[92:95], v[216:219], v[40:43]
	v_fma_f32 v97, v97, v154, v204
	s_mov_b32 s51, s50
	s_cbranch_scc0 .LBB0_413
	s_mov_b64 s[2:3], 0
